# p->bf16 conversion loop (layer 0): all 8 grid-strided pieces per thread loaded together instead of one exposed load per iteration
# speedup vs baseline: 1.0007x; 1.0007x over previous
.LBB0_672:
	v_lshl_add_u64 v[2:3], v[0:1], 4, s[6:7]
	v_lshl_add_u64 v[4:5], v[0:1], 3, s[12:13]
	s_mov_b64 s[16:17], 0x200000
	global_load_dwordx4 v[40:43], v[2:3], off
	v_lshl_add_u64 v[2:3], v[2:3], 0, s[16:17]
	global_load_dwordx4 v[44:47], v[2:3], off
	v_lshl_add_u64 v[2:3], v[2:3], 0, s[16:17]
	global_load_dwordx4 v[48:51], v[2:3], off
	v_lshl_add_u64 v[2:3], v[2:3], 0, s[16:17]
	global_load_dwordx4 v[52:55], v[2:3], off
	v_lshl_add_u64 v[2:3], v[2:3], 0, s[16:17]
	global_load_dwordx4 v[56:59], v[2:3], off
	v_lshl_add_u64 v[2:3], v[2:3], 0, s[16:17]
	global_load_dwordx4 v[60:63], v[2:3], off
	v_lshl_add_u64 v[2:3], v[2:3], 0, s[16:17]
	global_load_dwordx4 v[64:67], v[2:3], off
	v_lshl_add_u64 v[2:3], v[2:3], 0, s[16:17]
	global_load_dwordx4 v[68:71], v[2:3], off
	s_mov_b64 s[16:17], 0x100000
	s_waitcnt vmcnt(7)
	v_bfe_u32 v6, v40, 16, 1
	v_add3_u32 v40, v40, v6, s43
	v_bfe_u32 v6, v41, 16, 1
	v_lshrrev_b32_e32 v40, 16, v40
	v_add3_u32 v41, v41, v6, s43
	v_and_or_b32 v40, v41, s33, v40
	v_bfe_u32 v6, v42, 16, 1
	v_add3_u32 v42, v42, v6, s43
	v_bfe_u32 v6, v43, 16, 1
	v_lshrrev_b32_e32 v42, 16, v42
	v_add3_u32 v43, v43, v6, s43
	v_and_or_b32 v41, v43, s33, v42
	global_store_dwordx2 v[4:5], v[40:41], off
	v_lshl_add_u64 v[4:5], v[4:5], 0, s[16:17]
	s_waitcnt vmcnt(7)
	v_bfe_u32 v6, v44, 16, 1
	v_add3_u32 v44, v44, v6, s43
	v_bfe_u32 v6, v45, 16, 1
	v_lshrrev_b32_e32 v44, 16, v44
	v_add3_u32 v45, v45, v6, s43
	v_and_or_b32 v44, v45, s33, v44
	v_bfe_u32 v6, v46, 16, 1
	v_add3_u32 v46, v46, v6, s43
	v_bfe_u32 v6, v47, 16, 1
	v_lshrrev_b32_e32 v46, 16, v46
	v_add3_u32 v47, v47, v6, s43
	v_and_or_b32 v45, v47, s33, v46
	global_store_dwordx2 v[4:5], v[44:45], off
	v_lshl_add_u64 v[4:5], v[4:5], 0, s[16:17]
	s_waitcnt vmcnt(7)
	v_bfe_u32 v6, v48, 16, 1
	v_add3_u32 v48, v48, v6, s43
	v_bfe_u32 v6, v49, 16, 1
	v_lshrrev_b32_e32 v48, 16, v48
	v_add3_u32 v49, v49, v6, s43
	v_and_or_b32 v48, v49, s33, v48
	v_bfe_u32 v6, v50, 16, 1
	v_add3_u32 v50, v50, v6, s43
	v_bfe_u32 v6, v51, 16, 1
	v_lshrrev_b32_e32 v50, 16, v50
	v_add3_u32 v51, v51, v6, s43
	v_and_or_b32 v49, v51, s33, v50
	global_store_dwordx2 v[4:5], v[48:49], off
	v_lshl_add_u64 v[4:5], v[4:5], 0, s[16:17]
	s_waitcnt vmcnt(7)
	v_bfe_u32 v6, v52, 16, 1
	v_add3_u32 v52, v52, v6, s43
	v_bfe_u32 v6, v53, 16, 1
	v_lshrrev_b32_e32 v52, 16, v52
	v_add3_u32 v53, v53, v6, s43
	v_and_or_b32 v52, v53, s33, v52
	v_bfe_u32 v6, v54, 16, 1
	v_add3_u32 v54, v54, v6, s43
	v_bfe_u32 v6, v55, 16, 1
	v_lshrrev_b32_e32 v54, 16, v54
	v_add3_u32 v55, v55, v6, s43
	v_and_or_b32 v53, v55, s33, v54
	global_store_dwordx2 v[4:5], v[52:53], off
	v_lshl_add_u64 v[4:5], v[4:5], 0, s[16:17]
	s_waitcnt vmcnt(7)
	v_bfe_u32 v6, v56, 16, 1
	v_add3_u32 v56, v56, v6, s43
	v_bfe_u32 v6, v57, 16, 1
	v_lshrrev_b32_e32 v56, 16, v56
	v_add3_u32 v57, v57, v6, s43
	v_and_or_b32 v56, v57, s33, v56
	v_bfe_u32 v6, v58, 16, 1
	v_add3_u32 v58, v58, v6, s43
	v_bfe_u32 v6, v59, 16, 1
	v_lshrrev_b32_e32 v58, 16, v58
	v_add3_u32 v59, v59, v6, s43
	v_and_or_b32 v57, v59, s33, v58
	global_store_dwordx2 v[4:5], v[56:57], off
	v_lshl_add_u64 v[4:5], v[4:5], 0, s[16:17]
	s_waitcnt vmcnt(7)
	v_bfe_u32 v6, v60, 16, 1
	v_add3_u32 v60, v60, v6, s43
	v_bfe_u32 v6, v61, 16, 1
	v_lshrrev_b32_e32 v60, 16, v60
	v_add3_u32 v61, v61, v6, s43
	v_and_or_b32 v60, v61, s33, v60
	v_bfe_u32 v6, v62, 16, 1
	v_add3_u32 v62, v62, v6, s43
	v_bfe_u32 v6, v63, 16, 1
	v_lshrrev_b32_e32 v62, 16, v62
	v_add3_u32 v63, v63, v6, s43
	v_and_or_b32 v61, v63, s33, v62
	global_store_dwordx2 v[4:5], v[60:61], off
	v_lshl_add_u64 v[4:5], v[4:5], 0, s[16:17]
	s_waitcnt vmcnt(7)
	v_bfe_u32 v6, v64, 16, 1
	v_add3_u32 v64, v64, v6, s43
	v_bfe_u32 v6, v65, 16, 1
	v_lshrrev_b32_e32 v64, 16, v64
	v_add3_u32 v65, v65, v6, s43
	v_and_or_b32 v64, v65, s33, v64
	v_bfe_u32 v6, v66, 16, 1
	v_add3_u32 v66, v66, v6, s43
	v_bfe_u32 v6, v67, 16, 1
	v_lshrrev_b32_e32 v66, 16, v66
	v_add3_u32 v67, v67, v6, s43
	v_and_or_b32 v65, v67, s33, v66
	global_store_dwordx2 v[4:5], v[64:65], off
	v_lshl_add_u64 v[4:5], v[4:5], 0, s[16:17]
	s_waitcnt vmcnt(7)
	v_bfe_u32 v6, v68, 16, 1
	v_add3_u32 v68, v68, v6, s43
	v_bfe_u32 v6, v69, 16, 1
	v_lshrrev_b32_e32 v68, 16, v68
	v_add3_u32 v69, v69, v6, s43
	v_and_or_b32 v68, v69, s33, v68
	v_bfe_u32 v6, v70, 16, 1
	v_add3_u32 v70, v70, v6, s43
	v_bfe_u32 v6, v71, 16, 1
	v_lshrrev_b32_e32 v70, 16, v70
	v_add3_u32 v71, v71, v6, s43
	v_and_or_b32 v69, v71, s33, v70
	global_store_dwordx2 v[4:5], v[68:69], off
